# in-proj prefetched-tile wait made exact: vmcnt(16) after 16 epilogue stores, vmcnt(8) when the wave's second column half is past 2784 (s32 doubled on that path)
# baseline (speedup 1.0000x reference)
; DI void phase_inproj(const Params& p, int layer, char* lds) {
;     ...
;   for (int u = bl; u < per_x; u += nbl) {
;     const int lr = u / NTN, nt = u % NTN;
;     const int mt = xcd_ok ? lr * 8 + xj : lr, m0 = mt * 256, n0 = nt * 256;
;     const int nvalid = (DIN - n0) < 256 ? (DIN - n0) : 256;
;     (void)nvalid;
;     f32x4 acc[2][2][4][2];
; #pragma unroll
;     for (int ai = 0; ai < 2; ++ai)
; #pragma unroll
;       for (int bj = 0; bj < 2; ++bj)
; #pragma unroll
;         for (int m = 0; m < 4; ++m)
; #pragma unroll
;           for (int n = 0; n < 2; ++n) acc[ai][bj][m][n] = (f32x4){0.f, 0.f, 0.f, 0.f};
;     gemm8p(xb, wt, m0, n0, acc);
;     const int wr8 = w >> 2, wc8 = w & 3, fr = lane & 15, fq = lane >> 4;
; #pragma unroll
;     for (int bj = 0; bj < 2; ++bj)
; #pragma unroll
;       for (int n = 0; n < 2; ++n) {
;         const int cw = n0 + bj * 128 + wc8 * 32 + n * 16, col = cw + fr;
;         u16* dst = H + cw; int dstr = DIN;
;         {
;           const int bb = m0 / S;
;           if (cw >= C_DK && cw < C_DV) { const int o = cw - C_DK; dst = (u16*)(p.ws + OFF_DK) + ((size_t)(bb * 3 * S + (o >> 6) * S) << 6) + (o & 63); dstr = 64; }
;           else if (cw >= C_DV && cw < C_SQ) { const int o = cw - C_DV; dst = (u16*)(p.ws + OFF_DV) + ((size_t)(bb * 3 * S + (o >> 6) * S) << 6) + (o & 63); dstr = 64; }
;           else if (cw >= C_SK && cw < C_SV) { const int o = cw - C_SK; dst = (u16*)(p.ws + OFF_SK) + ((size_t)(bb * 1 * S + (o >> 6) * S) << 6) + (o & 63); dstr = 64; }
;           else if (cw >= C_SV && cw < C_GATE) { const int o = cw - C_SV; dst = (u16*)(p.ws + OFF_SV) + ((size_t)(bb * 1 * S + (o >> 6) * S) << 6) + (o & 63); dstr = 64; }
;         }
;         if (cw < DIN) {
;           float sc = 1.f;
;           if (col >= C_DQ && col < C_DK) sc = SC_DQ;
;           if (col >= C_SQ && col < C_SK) sc = SC_SQ;
;           const bool gate = col >= C_GATE;
; #pragma unroll
;           for (int ai = 0; ai < 2; ++ai)
; #pragma unroll
;             for (int m = 0; m < 4; ++m) {
; #pragma unroll
;               for (int j = 0; j < 4; ++j) {
;                 const int row = m0 + ai * 128 + wr8 * 64 + m * 16 + fq * 4 + j;
;                 float v = acc[ai][bj][m][n][j] * sc;
;                 if (gate) v = v * __builtin_amdgcn_rcpf(1.f + __expf(-v));
;                 dst[(size_t)row * dstr + fr] = f2bf(v);
;               }
.Lipf_w4h:
	v_cmp_eq_u32_e64 vcc, s32, 2
	s_cbranch_vccnz .Lipf_w4h8
	s_waitcnt vmcnt(16)
	s_branch .Lipf_w4d

; DI void phase_inproj(const Params& p, int layer, char* lds) {
;     ...
;     for (int bj = 0; bj < 2; ++bj)
; #pragma unroll
;       for (int n = 0; n < 2; ++n) {
;         const int cw = n0 + bj * 128 + wc8 * 32 + n * 16, col = cw + fr;
;         u16* dst = H + cw; int dstr = DIN;
;         {
;           const int bb = m0 / S;
;           if (cw >= C_DK && cw < C_DV) { const int o = cw - C_DK; dst = (u16*)(p.ws + OFF_DK) + ((size_t)(bb * 3 * S + (o >> 6) * S) << 6) + (o & 63); dstr = 64; }
;           else if (cw >= C_DV && cw < C_SQ) { const int o = cw - C_DV; dst = (u16*)(p.ws + OFF_DV) + ((size_t)(bb * 3 * S + (o >> 6) * S) << 6) + (o & 63); dstr = 64; }
;           else if (cw >= C_SK && cw < C_SV) { const int o = cw - C_SK; dst = (u16*)(p.ws + OFF_SK) + ((size_t)(bb * 1 * S + (o >> 6) * S) << 6) + (o & 63); dstr = 64; }
;           else if (cw >= C_SV && cw < C_GATE) { const int o = cw - C_SV; dst = (u16*)(p.ws + OFF_SV) + ((size_t)(bb * 1 * S + (o >> 6) * S) << 6) + (o & 63); dstr = 64; }
;         }
;         if (cw < DIN) {
.Lipe1_skip:
	s_lshl_b32 s32, s32, 1
	s_mov_b64 s[4:5], -1
	s_branch .LBB0_81
